# decode-sample mixer items reordered: decode-attention items dispatched before the streaming state items
# speedup vs baseline: 1.0593x; 1.0017x over previous
; DI void att_prompt_item(char* shm, const Params& P, int l, int hf, int b, int blk, int kvh) {
;     ...
;   const int lr0 = b * 2048 + blk * 128 - hf * HALF_ROWS;
;   const int g = w >> 1, qh = kvh * 4 + g, r = lane & 31, h = lane >> 5;
;   bf16x8 qall[2][4];
;   _Pragma("unroll") for (int qq = 0; qq < 2; ++qq) { const u16* qp = Z + (size_t)(lr0 + ((w & 1) * 2 + qq) * 32 + r) * ZS + C_AQ + qh * 64;
;     _Pragma("unroll") for (int s = 0; s < 4; ++s) qall[qq][s] = ld8(qp + 16 * s + 8 * h); }
;   const float sink = P.sinks[l * 16 + qh];
;   const float btv = bt[(tid & 127) * 16 + kvh * 4 + (tid >> 7)];
;   __syncthreads();
;   {
;     bf16x8 kr[4], vr[4];
;     _Pragma("unroll") for (int it = 0; it < 4; ++it) { const int c = tid + it * NT, key = c >> 3, part = c & 7;
;       if (blk > 0 || key >= 128) { const u16* src = Z + (size_t)(lr0 - 128 + key) * ZS; kr[it] = ld8(src + C_AK + kvh * 64 + part * 8); vr[it] = ld8(src + C_AV + kvh * 64 + part * 8); }
; DI void mixer_phase(char* shm, const Params& P, int l, int hf, int ph) {
;     ...
;     __syncthreads();
;     if (threadIdx.x == 0) s_item = (int)atomicAdd(ctr, 1u);
;     __syncthreads();
;     int it = s_item;
;     if (it >= nitems) break;
;     const int nsamp = hf ? 512 : 0;
;     if (it < 128) { ssd_prompt_item(shm, P, l, hf, hf * 8 + (it >> 4), it & 15); }
;     else if ((it -= 128) < 64) { ret_prompt_item(shm, P, l, hf, hf * 8 + (it >> 3), it & 7); }
;     else if ((it -= 64) < nsamp) {
;       if (it < 256) { ssd_sample_item(shm, P, l, it >> 1, it & 1); }
;       else if ((it -= 256) < 128) { ret_sample_item(shm, P, l, it); }
;       else { it -= 128; att_sample_item(shm, P, l, it); }
;     }
;     else { it -= nsamp; att_prompt_item(shm, P, l, hf, hf * 8 + (it >> 6), (it >> 2) & 15, it & 3); }
.LBB0_68:
	s_or_b64 exec, exec, s[0:1]
	s_waitcnt lgkmcnt(0)
	s_barrier
	s_waitcnt vmcnt(0)
	ds_read_b32 v0, v65
	v_readlane_b32 s0, v255, 13
	s_waitcnt lgkmcnt(0)
	v_readfirstlane_b32 s97, v0
	v_cmp_le_i32_e32 vcc, s0, v0
	s_mov_b64 s[0:1], -1
	s_cbranch_vccnz .LBB0_63
	v_readlane_b32 s4, v255, 12
	s_add_i32 s5, s97, 0xffffff40
	s_cmp_lt_u32 s5, s4
	s_cbranch_scc0 .Lmix_noremap
	s_add_i32 s5, s5, 0x180
	s_and_b32 s5, s5, 0x1ff
	s_add_i32 s97, s5, 0xc0
.Lmix_noremap:
	s_cmpk_gt_i32 s97, 0x7f
	s_cbranch_scc0 .LBB0_240
	s_cmpk_gt_u32 s97, 0xbf
	s_cbranch_scc0 .LBB0_224
	s_add_i32 s3, s97, 0xffffff40
	v_readlane_b32 s0, v255, 12
	s_cmp_ge_i32 s3, s0
	s_mov_b64 s[0:1], -1
	s_cbranch_scc0 .LBB0_106
	v_readlane_b32 s0, v255, 12
	s_sub_i32 s0, s3, s0
	s_lshr_b32 s43, s0, 6
	v_readlane_b32 s0, v255, 14
	s_add_i32 s43, s43, s0
	s_mov_b64 s[0:1], s[74:75]
	s_mov_b64 s[4:5], s[74:75]
	v_mov_b32_e32 v85, v242
	s_bfe_u32 s44, s97, 0x40002
	s_and_b32 s9, s97, 3
	s_add_u32 s0, s0, 0xad44000
	v_ashrrev_i32_e32 v36, 6, v85
	v_ashrrev_i32_e32 v38, 7, v85
	s_waitcnt vmcnt(2)
	v_lshl_add_u32 v4, s9, 2, v38
	v_lshlrev_b32_e32 v0, 1, v36
	s_addc_u32 s1, s1, 0
	s_lshl_b32 s6, s43, 11
	v_and_b32_e32 v97, 2, v0
	v_lshlrev_b32_e32 v0, 6, v4
	s_lshl_b32 s7, s44, 7
	s_sub_i32 s6, s6, s77
	v_bfe_u32 v35, v85, 5, 1
	v_ashrrev_i32_e32 v1, 31, v0
	s_or_b32 s46, s6, s7
	v_and_b32_e32 v94, 31, v85
	v_lshl_add_u64 v[82:83], v[0:1], 1, s[0:1]
	v_lshlrev_b32_e32 v64, 4, v35
	v_lshlrev_b32_e32 v34, 5, v97
	v_lshl_add_u64 v[0:1], v[82:83], 0, v[64:65]
	v_or3_b32 v37, v34, v94, s46
	v_mad_i64_i32 v[2:3], s[6:7], v37, s33, v[0:1]
	global_load_dwordx4 v[66:69], v[2:3], off
	global_load_dwordx4 v[70:73], v[2:3], off offset:32
	global_load_dwordx4 v[74:77], v[2:3], off offset:64
	global_load_dwordx4 v[78:81], v[2:3], off offset:96
	v_or_b32_e32 v2, 32, v37
	v_mad_i64_i32 v[0:1], s[6:7], v2, s33, v[0:1]
	global_load_dwordx4 v[48:51], v[0:1], off
	global_load_dwordx4 v[52:55], v[0:1], off offset:32
	global_load_dwordx4 v[56:59], v[0:1], off offset:64
	global_load_dwordx4 v[60:63], v[0:1], off offset:96
	v_add_u32_e32 v0, s83, v4
	v_readlane_b32 s12, v253, 34
	v_ashrrev_i32_e32 v1, 31, v0
	v_readlane_b32 s16, v253, 38
	v_readlane_b32 s17, v253, 39
	v_and_b32_e32 v40, 0x7f, v85
	s_cmp_lg_u32 s44, 0
	v_lshl_add_u64 v[0:1], v[0:1], 2, s[16:17]
	global_load_dword v39, v[0:1], off
	v_lshl_add_u32 v0, v40, 4, v4
	v_ashrrev_i32_e32 v1, 31, v0
	v_lshl_add_u64 v[0:1], v[0:1], 2, s[4:5]
	global_load_dword v41, v[0:1], off offset:256
	v_lshlrev_b32_e32 v0, 3, v85
	v_ashrrev_i32_e32 v42, 3, v85
	s_movk_i32 s6, 0x7f
	s_cselect_b64 s[4:5], -1, 0
	v_and_b32_e32 v43, 56, v0
	v_cmp_lt_i32_e32 vcc, s6, v42
	v_mov_b32_e32 v4, 0
	s_add_i32 s8, s46, 0xffffff80
	s_lshl_b32 s45, s9, 6
	s_or_b64 s[10:11], s[4:5], vcc
	v_lshlrev_b32_e32 v32, 1, v43
	v_mov_b32_e32 v5, v4
	v_mov_b32_e32 v6, v4
	v_mov_b32_e32 v7, v4
	v_mov_b32_e32 v0, v4
	v_mov_b32_e32 v1, v4
	v_mov_b32_e32 v2, v4
	v_mov_b32_e32 v3, v4
	v_readlane_b32 s13, v253, 35
	v_readlane_b32 s14, v253, 36
	v_readlane_b32 s15, v253, 37
	v_readlane_b32 s18, v253, 40
	v_readlane_b32 s19, v253, 41
	v_readlane_b32 s20, v253, 42
	v_readlane_b32 s21, v253, 43
	v_readlane_b32 s22, v253, 44
	v_readlane_b32 s23, v253, 45
	v_readlane_b32 s24, v253, 46
	v_readlane_b32 s25, v253, 47
	v_readlane_b32 s26, v253, 48
	v_readlane_b32 s27, v253, 49
	s_barrier
	s_and_saveexec_b64 s[6:7], s[10:11]
	s_cbranch_execz .LBB0_74
	v_add_u32_e32 v2, s8, v42
	v_mov_b64_e32 v[0:1], s[0:1]
	v_mad_i64_i32 v[0:1], s[10:11], v2, s33, v[0:1]
	s_lshl_b32 s84, s45, 1
	v_lshl_add_u64 v[0:1], v[0:1], 0, s[84:85]
	v_mov_b32_e32 v33, v65
	v_lshl_add_u64 v[0:1], v[0:1], 0, v[32:33]
	global_load_dwordx4 v[4:7], v[0:1], off offset:2048
	s_nop 0
	global_load_dwordx4 v[0:3], v[0:1], off offset:2560
